# P1 gate epilogue by hand (folded bias/scale fma, SDWA byte packing) plus lane exchange so quads store 32 contiguous bytes, stores pipelined
# speedup vs baseline: 1.0081x; 1.0081x over previous
.LBB0_220:
	s_cmp_lt_i32 s84, 3
	s_cbranch_scc1 .LBB0_262
	s_cmp_lg_u32 s84, 3
	s_cbranch_scc0 .LBB0_223
	s_add_i32 s16, s84, -4
	s_add_i32 vcc_lo, s84, -8
	s_lshl_b32 s48, s16, 8
	s_cmp_lt_u32 s84, 8
	s_cselect_b32 s4, s30, s66
	s_cselect_b32 s5, s31, s67
	s_cselect_b32 vcc_lo, s16, vcc_lo
	s_lshl_b32 vcc_lo, vcc_lo, 8
	v_lshl_add_u64 v[132:133], s[48:49], 2, v[186:187]
	global_load_dwordx4 v[136:139], v[132:133], off
	global_load_dwordx4 v[140:143], v[132:133], off offset:16
	global_load_dwordx4 v[144:147], v[132:133], off offset:512
	global_load_dwordx4 v[148:151], v[132:133], off offset:528
	v_and_b32_e32 v128, 3, v209
	v_bfe_u32 v129, v209, 4, 2
	v_and_or_b32 v129, v209, 12, v129
	v_lshl_or_b32 v199, v128, 4, v129
	v_lshlrev_b32_e32 v199, 2, v199
	v_and_or_b32 v129, v198, -16, v129
	v_and_b32_e32 v130, 0x60, v178
	v_lshl_or_b32 v130, v128, 3, v130
	v_lshl_add_u32 v152, v129, 10, v130
	v_add_u32_e32 v152, vcc_lo, v152
	s_mov_b32 vcc_lo, 0xbfb8aa3b
	v_add_u32_e32 v153, 0x4000, v152
	v_add_u32_e32 v154, 0x8000, v152
	v_add_u32_e32 v155, 0xc000, v152
	v_add_u32_e32 v156, 0x20000, v152
	v_add_u32_e32 v157, 0x24000, v152
	v_add_u32_e32 v158, 0x28000, v152
	v_add_u32_e32 v159, 0x2c000, v152
	s_waitcnt vmcnt(0)
	v_mul_f32_e32 v136, 0xbfb8aa3b, v136
	v_mul_f32_e32 v137, 0xbfb8aa3b, v137
	v_mul_f32_e32 v138, 0xbfb8aa3b, v138
	v_mul_f32_e32 v139, 0xbfb8aa3b, v139
	v_mul_f32_e32 v140, 0xbfb8aa3b, v140
	v_mul_f32_e32 v141, 0xbfb8aa3b, v141
	v_mul_f32_e32 v142, 0xbfb8aa3b, v142
	v_mul_f32_e32 v143, 0xbfb8aa3b, v143
	v_mul_f32_e32 v144, 0xbfb8aa3b, v144
	v_mul_f32_e32 v145, 0xbfb8aa3b, v145
	v_mul_f32_e32 v146, 0xbfb8aa3b, v146
	v_mul_f32_e32 v147, 0xbfb8aa3b, v147
	v_mul_f32_e32 v148, 0xbfb8aa3b, v148
	v_mul_f32_e32 v149, 0xbfb8aa3b, v149
	v_mul_f32_e32 v150, 0xbfb8aa3b, v150
	v_mul_f32_e32 v151, 0xbfb8aa3b, v151
	v_pk_fma_f32 v[120:121], v[120:121], vcc, v[136:137] op_sel_hi:[1,0,1]
	v_pk_fma_f32 v[122:123], v[122:123], vcc, v[138:139] op_sel_hi:[1,0,1]
	v_pk_fma_f32 v[124:125], v[124:125], vcc, v[140:141] op_sel_hi:[1,0,1]
	v_pk_fma_f32 v[126:127], v[126:127], vcc, v[142:143] op_sel_hi:[1,0,1]
	v_exp_f32_e32 v120, v120
	v_exp_f32_e32 v121, v121
	v_exp_f32_e32 v122, v122
	v_exp_f32_e32 v123, v123
	v_exp_f32_e32 v124, v124
	v_exp_f32_e32 v125, v125
	v_exp_f32_e32 v126, v126
	v_exp_f32_e32 v127, v127
	v_pk_add_f32 v[120:121], v[120:121], 1.0 op_sel_hi:[1,0]
	v_pk_add_f32 v[122:123], v[122:123], 1.0 op_sel_hi:[1,0]
	v_pk_add_f32 v[124:125], v[124:125], 1.0 op_sel_hi:[1,0]
	v_pk_add_f32 v[126:127], v[126:127], 1.0 op_sel_hi:[1,0]
	v_rcp_f32_e32 v120, v120
	v_rcp_f32_e32 v121, v121
	v_rcp_f32_e32 v122, v122
	v_rcp_f32_e32 v123, v123
	v_rcp_f32_e32 v124, v124
	v_rcp_f32_e32 v125, v125
	v_rcp_f32_e32 v126, v126
	v_rcp_f32_e32 v127, v127
	v_pk_fma_f32 v[120:121], v[120:121], s[20:21], 0.5 op_sel_hi:[1,0,0]
	v_pk_fma_f32 v[122:123], v[122:123], s[20:21], 0.5 op_sel_hi:[1,0,0]
	v_pk_fma_f32 v[124:125], v[124:125], s[20:21], 0.5 op_sel_hi:[1,0,0]
	v_pk_fma_f32 v[126:127], v[126:127], s[20:21], 0.5 op_sel_hi:[1,0,0]
	v_cvt_u32_f32_e32 v128, v120
	v_cvt_u32_f32_e32 v129, v124
	v_cvt_u32_f32_sdwa v128, v121 dst_sel:BYTE_1 dst_unused:UNUSED_PRESERVE src0_sel:DWORD
	v_cvt_u32_f32_sdwa v129, v125 dst_sel:BYTE_1 dst_unused:UNUSED_PRESERVE src0_sel:DWORD
	v_cvt_u32_f32_sdwa v128, v122 dst_sel:BYTE_2 dst_unused:UNUSED_PRESERVE src0_sel:DWORD
	v_cvt_u32_f32_sdwa v129, v126 dst_sel:BYTE_2 dst_unused:UNUSED_PRESERVE src0_sel:DWORD
	v_cvt_u32_f32_sdwa v128, v123 dst_sel:BYTE_3 dst_unused:UNUSED_PRESERVE src0_sel:DWORD
	v_cvt_u32_f32_sdwa v129, v127 dst_sel:BYTE_3 dst_unused:UNUSED_PRESERVE src0_sel:DWORD
	s_nop 0
	ds_bpermute_b32 v128, v199, v128
	ds_bpermute_b32 v129, v199, v129
	v_pk_fma_f32 v[116:117], v[116:117], vcc, v[144:145] op_sel_hi:[1,0,1]
	v_pk_fma_f32 v[118:119], v[118:119], vcc, v[146:147] op_sel_hi:[1,0,1]
	v_pk_fma_f32 v[112:113], v[112:113], vcc, v[148:149] op_sel_hi:[1,0,1]
	v_pk_fma_f32 v[114:115], v[114:115], vcc, v[150:151] op_sel_hi:[1,0,1]
	v_exp_f32_e32 v116, v116
	v_exp_f32_e32 v117, v117
	v_exp_f32_e32 v118, v118
	v_exp_f32_e32 v119, v119
	v_exp_f32_e32 v112, v112
	v_exp_f32_e32 v113, v113
	v_exp_f32_e32 v114, v114
	v_exp_f32_e32 v115, v115
	v_pk_add_f32 v[116:117], v[116:117], 1.0 op_sel_hi:[1,0]
	v_pk_add_f32 v[118:119], v[118:119], 1.0 op_sel_hi:[1,0]
	v_pk_add_f32 v[112:113], v[112:113], 1.0 op_sel_hi:[1,0]
	v_pk_add_f32 v[114:115], v[114:115], 1.0 op_sel_hi:[1,0]
	v_rcp_f32_e32 v116, v116
	v_rcp_f32_e32 v117, v117
	v_rcp_f32_e32 v118, v118
	v_rcp_f32_e32 v119, v119
	v_rcp_f32_e32 v112, v112
	v_rcp_f32_e32 v113, v113
	v_rcp_f32_e32 v114, v114
	v_rcp_f32_e32 v115, v115
	v_pk_fma_f32 v[116:117], v[116:117], s[20:21], 0.5 op_sel_hi:[1,0,0]
	v_pk_fma_f32 v[118:119], v[118:119], s[20:21], 0.5 op_sel_hi:[1,0,0]
	v_pk_fma_f32 v[112:113], v[112:113], s[20:21], 0.5 op_sel_hi:[1,0,0]
	v_pk_fma_f32 v[114:115], v[114:115], s[20:21], 0.5 op_sel_hi:[1,0,0]
	v_cvt_u32_f32_e32 v130, v116
	v_cvt_u32_f32_e32 v131, v112
	v_cvt_u32_f32_sdwa v130, v117 dst_sel:BYTE_1 dst_unused:UNUSED_PRESERVE src0_sel:DWORD
	v_cvt_u32_f32_sdwa v131, v113 dst_sel:BYTE_1 dst_unused:UNUSED_PRESERVE src0_sel:DWORD
	v_cvt_u32_f32_sdwa v130, v118 dst_sel:BYTE_2 dst_unused:UNUSED_PRESERVE src0_sel:DWORD
	v_cvt_u32_f32_sdwa v131, v114 dst_sel:BYTE_2 dst_unused:UNUSED_PRESERVE src0_sel:DWORD
	v_cvt_u32_f32_sdwa v130, v119 dst_sel:BYTE_3 dst_unused:UNUSED_PRESERVE src0_sel:DWORD
	v_cvt_u32_f32_sdwa v131, v115 dst_sel:BYTE_3 dst_unused:UNUSED_PRESERVE src0_sel:DWORD
	s_nop 0
	ds_bpermute_b32 v130, v199, v130
	ds_bpermute_b32 v131, v199, v131
	v_pk_fma_f32 v[108:109], v[108:109], vcc, v[136:137] op_sel_hi:[1,0,1]
	v_pk_fma_f32 v[110:111], v[110:111], vcc, v[138:139] op_sel_hi:[1,0,1]
	v_pk_fma_f32 v[104:105], v[104:105], vcc, v[140:141] op_sel_hi:[1,0,1]
	v_pk_fma_f32 v[106:107], v[106:107], vcc, v[142:143] op_sel_hi:[1,0,1]
	v_exp_f32_e32 v108, v108
	v_exp_f32_e32 v109, v109
	v_exp_f32_e32 v110, v110
	v_exp_f32_e32 v111, v111
	v_exp_f32_e32 v104, v104
	v_exp_f32_e32 v105, v105
	v_exp_f32_e32 v106, v106
	v_exp_f32_e32 v107, v107
	v_pk_add_f32 v[108:109], v[108:109], 1.0 op_sel_hi:[1,0]
	v_pk_add_f32 v[110:111], v[110:111], 1.0 op_sel_hi:[1,0]
	v_pk_add_f32 v[104:105], v[104:105], 1.0 op_sel_hi:[1,0]
	v_pk_add_f32 v[106:107], v[106:107], 1.0 op_sel_hi:[1,0]
	v_rcp_f32_e32 v108, v108
	v_rcp_f32_e32 v109, v109
	v_rcp_f32_e32 v110, v110
	v_rcp_f32_e32 v111, v111
	v_rcp_f32_e32 v104, v104
	v_rcp_f32_e32 v105, v105
	v_rcp_f32_e32 v106, v106
	v_rcp_f32_e32 v107, v107
	v_pk_fma_f32 v[108:109], v[108:109], s[20:21], 0.5 op_sel_hi:[1,0,0]
	v_pk_fma_f32 v[110:111], v[110:111], s[20:21], 0.5 op_sel_hi:[1,0,0]
	v_pk_fma_f32 v[104:105], v[104:105], s[20:21], 0.5 op_sel_hi:[1,0,0]
	v_pk_fma_f32 v[106:107], v[106:107], s[20:21], 0.5 op_sel_hi:[1,0,0]
	v_cvt_u32_f32_e32 v134, v108
	v_cvt_u32_f32_e32 v135, v104
	v_cvt_u32_f32_sdwa v134, v109 dst_sel:BYTE_1 dst_unused:UNUSED_PRESERVE src0_sel:DWORD
	v_cvt_u32_f32_sdwa v135, v105 dst_sel:BYTE_1 dst_unused:UNUSED_PRESERVE src0_sel:DWORD
	v_cvt_u32_f32_sdwa v134, v110 dst_sel:BYTE_2 dst_unused:UNUSED_PRESERVE src0_sel:DWORD
	v_cvt_u32_f32_sdwa v135, v106 dst_sel:BYTE_2 dst_unused:UNUSED_PRESERVE src0_sel:DWORD
	v_cvt_u32_f32_sdwa v134, v111 dst_sel:BYTE_3 dst_unused:UNUSED_PRESERVE src0_sel:DWORD
	v_cvt_u32_f32_sdwa v135, v107 dst_sel:BYTE_3 dst_unused:UNUSED_PRESERVE src0_sel:DWORD
	s_nop 0
	ds_bpermute_b32 v134, v199, v134
	ds_bpermute_b32 v135, v199, v135
	s_waitcnt lgkmcnt(4)
	global_store_dwordx2 v152, v[128:129], s[4:5]
	v_pk_fma_f32 v[100:101], v[100:101], vcc, v[144:145] op_sel_hi:[1,0,1]
	v_pk_fma_f32 v[102:103], v[102:103], vcc, v[146:147] op_sel_hi:[1,0,1]
	v_pk_fma_f32 v[96:97], v[96:97], vcc, v[148:149] op_sel_hi:[1,0,1]
	v_pk_fma_f32 v[98:99], v[98:99], vcc, v[150:151] op_sel_hi:[1,0,1]
	v_exp_f32_e32 v100, v100
	v_exp_f32_e32 v101, v101
	v_exp_f32_e32 v102, v102
	v_exp_f32_e32 v103, v103
	v_exp_f32_e32 v96, v96
	v_exp_f32_e32 v97, v97
	v_exp_f32_e32 v98, v98
	v_exp_f32_e32 v99, v99
	v_pk_add_f32 v[100:101], v[100:101], 1.0 op_sel_hi:[1,0]
	v_pk_add_f32 v[102:103], v[102:103], 1.0 op_sel_hi:[1,0]
	v_pk_add_f32 v[96:97], v[96:97], 1.0 op_sel_hi:[1,0]
	v_pk_add_f32 v[98:99], v[98:99], 1.0 op_sel_hi:[1,0]
	v_rcp_f32_e32 v100, v100
	v_rcp_f32_e32 v101, v101
	v_rcp_f32_e32 v102, v102
	v_rcp_f32_e32 v103, v103
	v_rcp_f32_e32 v96, v96
	v_rcp_f32_e32 v97, v97
	v_rcp_f32_e32 v98, v98
	v_rcp_f32_e32 v99, v99
	v_pk_fma_f32 v[100:101], v[100:101], s[20:21], 0.5 op_sel_hi:[1,0,0]
	v_pk_fma_f32 v[102:103], v[102:103], s[20:21], 0.5 op_sel_hi:[1,0,0]
	v_pk_fma_f32 v[96:97], v[96:97], s[20:21], 0.5 op_sel_hi:[1,0,0]
	v_pk_fma_f32 v[98:99], v[98:99], s[20:21], 0.5 op_sel_hi:[1,0,0]
	v_cvt_u32_f32_e32 v160, v100
	v_cvt_u32_f32_e32 v161, v96
	v_cvt_u32_f32_sdwa v160, v101 dst_sel:BYTE_1 dst_unused:UNUSED_PRESERVE src0_sel:DWORD
	v_cvt_u32_f32_sdwa v161, v97 dst_sel:BYTE_1 dst_unused:UNUSED_PRESERVE src0_sel:DWORD
	v_cvt_u32_f32_sdwa v160, v102 dst_sel:BYTE_2 dst_unused:UNUSED_PRESERVE src0_sel:DWORD
	v_cvt_u32_f32_sdwa v161, v98 dst_sel:BYTE_2 dst_unused:UNUSED_PRESERVE src0_sel:DWORD
	v_cvt_u32_f32_sdwa v160, v103 dst_sel:BYTE_3 dst_unused:UNUSED_PRESERVE src0_sel:DWORD
	v_cvt_u32_f32_sdwa v161, v99 dst_sel:BYTE_3 dst_unused:UNUSED_PRESERVE src0_sel:DWORD
	s_nop 0
	ds_bpermute_b32 v160, v199, v160
	ds_bpermute_b32 v161, v199, v161
	s_waitcnt lgkmcnt(4)
	global_store_dwordx2 v152, v[130:131], s[4:5] offset:128
	v_pk_fma_f32 v[92:93], v[92:93], vcc, v[136:137] op_sel_hi:[1,0,1]
	v_pk_fma_f32 v[94:95], v[94:95], vcc, v[138:139] op_sel_hi:[1,0,1]
	v_pk_fma_f32 v[88:89], v[88:89], vcc, v[140:141] op_sel_hi:[1,0,1]
	v_pk_fma_f32 v[90:91], v[90:91], vcc, v[142:143] op_sel_hi:[1,0,1]
	v_exp_f32_e32 v92, v92
	v_exp_f32_e32 v93, v93
	v_exp_f32_e32 v94, v94
	v_exp_f32_e32 v95, v95
	v_exp_f32_e32 v88, v88
	v_exp_f32_e32 v89, v89
	v_exp_f32_e32 v90, v90
	v_exp_f32_e32 v91, v91
	v_pk_add_f32 v[92:93], v[92:93], 1.0 op_sel_hi:[1,0]
	v_pk_add_f32 v[94:95], v[94:95], 1.0 op_sel_hi:[1,0]
	v_pk_add_f32 v[88:89], v[88:89], 1.0 op_sel_hi:[1,0]
	v_pk_add_f32 v[90:91], v[90:91], 1.0 op_sel_hi:[1,0]
	v_rcp_f32_e32 v92, v92
	v_rcp_f32_e32 v93, v93
	v_rcp_f32_e32 v94, v94
	v_rcp_f32_e32 v95, v95
	v_rcp_f32_e32 v88, v88
	v_rcp_f32_e32 v89, v89
	v_rcp_f32_e32 v90, v90
	v_rcp_f32_e32 v91, v91
	v_pk_fma_f32 v[92:93], v[92:93], s[20:21], 0.5 op_sel_hi:[1,0,0]
	v_pk_fma_f32 v[94:95], v[94:95], s[20:21], 0.5 op_sel_hi:[1,0,0]
	v_pk_fma_f32 v[88:89], v[88:89], s[20:21], 0.5 op_sel_hi:[1,0,0]
	v_pk_fma_f32 v[90:91], v[90:91], s[20:21], 0.5 op_sel_hi:[1,0,0]
	v_cvt_u32_f32_e32 v128, v92
	v_cvt_u32_f32_e32 v129, v88
	v_cvt_u32_f32_sdwa v128, v93 dst_sel:BYTE_1 dst_unused:UNUSED_PRESERVE src0_sel:DWORD
	v_cvt_u32_f32_sdwa v129, v89 dst_sel:BYTE_1 dst_unused:UNUSED_PRESERVE src0_sel:DWORD
	v_cvt_u32_f32_sdwa v128, v94 dst_sel:BYTE_2 dst_unused:UNUSED_PRESERVE src0_sel:DWORD
	v_cvt_u32_f32_sdwa v129, v90 dst_sel:BYTE_2 dst_unused:UNUSED_PRESERVE src0_sel:DWORD
	v_cvt_u32_f32_sdwa v128, v95 dst_sel:BYTE_3 dst_unused:UNUSED_PRESERVE src0_sel:DWORD
	v_cvt_u32_f32_sdwa v129, v91 dst_sel:BYTE_3 dst_unused:UNUSED_PRESERVE src0_sel:DWORD
	s_nop 0
	ds_bpermute_b32 v128, v199, v128
	ds_bpermute_b32 v129, v199, v129
	s_waitcnt lgkmcnt(4)
	global_store_dwordx2 v153, v[134:135], s[4:5]
	v_pk_fma_f32 v[84:85], v[84:85], vcc, v[144:145] op_sel_hi:[1,0,1]
	v_pk_fma_f32 v[86:87], v[86:87], vcc, v[146:147] op_sel_hi:[1,0,1]
	v_pk_fma_f32 v[80:81], v[80:81], vcc, v[148:149] op_sel_hi:[1,0,1]
	v_pk_fma_f32 v[82:83], v[82:83], vcc, v[150:151] op_sel_hi:[1,0,1]
	v_exp_f32_e32 v84, v84
	v_exp_f32_e32 v85, v85
	v_exp_f32_e32 v86, v86
	v_exp_f32_e32 v87, v87
	v_exp_f32_e32 v80, v80
	v_exp_f32_e32 v81, v81
	v_exp_f32_e32 v82, v82
	v_exp_f32_e32 v83, v83
	v_pk_add_f32 v[84:85], v[84:85], 1.0 op_sel_hi:[1,0]
	v_pk_add_f32 v[86:87], v[86:87], 1.0 op_sel_hi:[1,0]
	v_pk_add_f32 v[80:81], v[80:81], 1.0 op_sel_hi:[1,0]
	v_pk_add_f32 v[82:83], v[82:83], 1.0 op_sel_hi:[1,0]
	v_rcp_f32_e32 v84, v84
	v_rcp_f32_e32 v85, v85
	v_rcp_f32_e32 v86, v86
	v_rcp_f32_e32 v87, v87
	v_rcp_f32_e32 v80, v80
	v_rcp_f32_e32 v81, v81
	v_rcp_f32_e32 v82, v82
	v_rcp_f32_e32 v83, v83
	v_pk_fma_f32 v[84:85], v[84:85], s[20:21], 0.5 op_sel_hi:[1,0,0]
	v_pk_fma_f32 v[86:87], v[86:87], s[20:21], 0.5 op_sel_hi:[1,0,0]
	v_pk_fma_f32 v[80:81], v[80:81], s[20:21], 0.5 op_sel_hi:[1,0,0]
	v_pk_fma_f32 v[82:83], v[82:83], s[20:21], 0.5 op_sel_hi:[1,0,0]
	v_cvt_u32_f32_e32 v130, v84
	v_cvt_u32_f32_e32 v131, v80
	v_cvt_u32_f32_sdwa v130, v85 dst_sel:BYTE_1 dst_unused:UNUSED_PRESERVE src0_sel:DWORD
	v_cvt_u32_f32_sdwa v131, v81 dst_sel:BYTE_1 dst_unused:UNUSED_PRESERVE src0_sel:DWORD
	v_cvt_u32_f32_sdwa v130, v86 dst_sel:BYTE_2 dst_unused:UNUSED_PRESERVE src0_sel:DWORD
	v_cvt_u32_f32_sdwa v131, v82 dst_sel:BYTE_2 dst_unused:UNUSED_PRESERVE src0_sel:DWORD
	v_cvt_u32_f32_sdwa v130, v87 dst_sel:BYTE_3 dst_unused:UNUSED_PRESERVE src0_sel:DWORD
	v_cvt_u32_f32_sdwa v131, v83 dst_sel:BYTE_3 dst_unused:UNUSED_PRESERVE src0_sel:DWORD
	s_nop 0
	ds_bpermute_b32 v130, v199, v130
	ds_bpermute_b32 v131, v199, v131
	s_waitcnt lgkmcnt(4)
	global_store_dwordx2 v153, v[160:161], s[4:5] offset:128
	v_pk_fma_f32 v[76:77], v[76:77], vcc, v[136:137] op_sel_hi:[1,0,1]
	v_pk_fma_f32 v[78:79], v[78:79], vcc, v[138:139] op_sel_hi:[1,0,1]
	v_pk_fma_f32 v[72:73], v[72:73], vcc, v[140:141] op_sel_hi:[1,0,1]
	v_pk_fma_f32 v[74:75], v[74:75], vcc, v[142:143] op_sel_hi:[1,0,1]
	v_exp_f32_e32 v76, v76
	v_exp_f32_e32 v77, v77
	v_exp_f32_e32 v78, v78
	v_exp_f32_e32 v79, v79
	v_exp_f32_e32 v72, v72
	v_exp_f32_e32 v73, v73
	v_exp_f32_e32 v74, v74
	v_exp_f32_e32 v75, v75
	v_pk_add_f32 v[76:77], v[76:77], 1.0 op_sel_hi:[1,0]
	v_pk_add_f32 v[78:79], v[78:79], 1.0 op_sel_hi:[1,0]
	v_pk_add_f32 v[72:73], v[72:73], 1.0 op_sel_hi:[1,0]
	v_pk_add_f32 v[74:75], v[74:75], 1.0 op_sel_hi:[1,0]
	v_rcp_f32_e32 v76, v76
	v_rcp_f32_e32 v77, v77
	v_rcp_f32_e32 v78, v78
	v_rcp_f32_e32 v79, v79
	v_rcp_f32_e32 v72, v72
	v_rcp_f32_e32 v73, v73
	v_rcp_f32_e32 v74, v74
	v_rcp_f32_e32 v75, v75
	v_pk_fma_f32 v[76:77], v[76:77], s[20:21], 0.5 op_sel_hi:[1,0,0]
	v_pk_fma_f32 v[78:79], v[78:79], s[20:21], 0.5 op_sel_hi:[1,0,0]
	v_pk_fma_f32 v[72:73], v[72:73], s[20:21], 0.5 op_sel_hi:[1,0,0]
	v_pk_fma_f32 v[74:75], v[74:75], s[20:21], 0.5 op_sel_hi:[1,0,0]
	v_cvt_u32_f32_e32 v134, v76
	v_cvt_u32_f32_e32 v135, v72
	v_cvt_u32_f32_sdwa v134, v77 dst_sel:BYTE_1 dst_unused:UNUSED_PRESERVE src0_sel:DWORD
	v_cvt_u32_f32_sdwa v135, v73 dst_sel:BYTE_1 dst_unused:UNUSED_PRESERVE src0_sel:DWORD
	v_cvt_u32_f32_sdwa v134, v78 dst_sel:BYTE_2 dst_unused:UNUSED_PRESERVE src0_sel:DWORD
	v_cvt_u32_f32_sdwa v135, v74 dst_sel:BYTE_2 dst_unused:UNUSED_PRESERVE src0_sel:DWORD
	v_cvt_u32_f32_sdwa v134, v79 dst_sel:BYTE_3 dst_unused:UNUSED_PRESERVE src0_sel:DWORD
	v_cvt_u32_f32_sdwa v135, v75 dst_sel:BYTE_3 dst_unused:UNUSED_PRESERVE src0_sel:DWORD
	s_nop 0
	ds_bpermute_b32 v134, v199, v134
	ds_bpermute_b32 v135, v199, v135
	s_waitcnt lgkmcnt(4)
	global_store_dwordx2 v154, v[128:129], s[4:5]
	v_pk_fma_f32 v[68:69], v[68:69], vcc, v[144:145] op_sel_hi:[1,0,1]
	v_pk_fma_f32 v[70:71], v[70:71], vcc, v[146:147] op_sel_hi:[1,0,1]
	v_pk_fma_f32 v[64:65], v[64:65], vcc, v[148:149] op_sel_hi:[1,0,1]
	v_pk_fma_f32 v[66:67], v[66:67], vcc, v[150:151] op_sel_hi:[1,0,1]
	v_exp_f32_e32 v68, v68
	v_exp_f32_e32 v69, v69
	v_exp_f32_e32 v70, v70
	v_exp_f32_e32 v71, v71
	v_exp_f32_e32 v64, v64
	v_exp_f32_e32 v65, v65
	v_exp_f32_e32 v66, v66
	v_exp_f32_e32 v67, v67
	v_pk_add_f32 v[68:69], v[68:69], 1.0 op_sel_hi:[1,0]
	v_pk_add_f32 v[70:71], v[70:71], 1.0 op_sel_hi:[1,0]
	v_pk_add_f32 v[64:65], v[64:65], 1.0 op_sel_hi:[1,0]
	v_pk_add_f32 v[66:67], v[66:67], 1.0 op_sel_hi:[1,0]
	v_rcp_f32_e32 v68, v68
	v_rcp_f32_e32 v69, v69
	v_rcp_f32_e32 v70, v70
	v_rcp_f32_e32 v71, v71
	v_rcp_f32_e32 v64, v64
	v_rcp_f32_e32 v65, v65
	v_rcp_f32_e32 v66, v66
	v_rcp_f32_e32 v67, v67
	v_pk_fma_f32 v[68:69], v[68:69], s[20:21], 0.5 op_sel_hi:[1,0,0]
	v_pk_fma_f32 v[70:71], v[70:71], s[20:21], 0.5 op_sel_hi:[1,0,0]
	v_pk_fma_f32 v[64:65], v[64:65], s[20:21], 0.5 op_sel_hi:[1,0,0]
	v_pk_fma_f32 v[66:67], v[66:67], s[20:21], 0.5 op_sel_hi:[1,0,0]
	v_cvt_u32_f32_e32 v160, v68
	v_cvt_u32_f32_e32 v161, v64
	v_cvt_u32_f32_sdwa v160, v69 dst_sel:BYTE_1 dst_unused:UNUSED_PRESERVE src0_sel:DWORD
	v_cvt_u32_f32_sdwa v161, v65 dst_sel:BYTE_1 dst_unused:UNUSED_PRESERVE src0_sel:DWORD
	v_cvt_u32_f32_sdwa v160, v70 dst_sel:BYTE_2 dst_unused:UNUSED_PRESERVE src0_sel:DWORD
	v_cvt_u32_f32_sdwa v161, v66 dst_sel:BYTE_2 dst_unused:UNUSED_PRESERVE src0_sel:DWORD
	v_cvt_u32_f32_sdwa v160, v71 dst_sel:BYTE_3 dst_unused:UNUSED_PRESERVE src0_sel:DWORD
	v_cvt_u32_f32_sdwa v161, v67 dst_sel:BYTE_3 dst_unused:UNUSED_PRESERVE src0_sel:DWORD
	s_nop 0
	ds_bpermute_b32 v160, v199, v160
	ds_bpermute_b32 v161, v199, v161
	s_waitcnt lgkmcnt(4)
	global_store_dwordx2 v154, v[130:131], s[4:5] offset:128
	v_pk_fma_f32 v[60:61], v[60:61], vcc, v[136:137] op_sel_hi:[1,0,1]
	v_pk_fma_f32 v[62:63], v[62:63], vcc, v[138:139] op_sel_hi:[1,0,1]
	v_pk_fma_f32 v[56:57], v[56:57], vcc, v[140:141] op_sel_hi:[1,0,1]
	v_pk_fma_f32 v[58:59], v[58:59], vcc, v[142:143] op_sel_hi:[1,0,1]
	v_exp_f32_e32 v60, v60
	v_exp_f32_e32 v61, v61
	v_exp_f32_e32 v62, v62
	v_exp_f32_e32 v63, v63
	v_exp_f32_e32 v56, v56
	v_exp_f32_e32 v57, v57
	v_exp_f32_e32 v58, v58
	v_exp_f32_e32 v59, v59
	v_pk_add_f32 v[60:61], v[60:61], 1.0 op_sel_hi:[1,0]
	v_pk_add_f32 v[62:63], v[62:63], 1.0 op_sel_hi:[1,0]
	v_pk_add_f32 v[56:57], v[56:57], 1.0 op_sel_hi:[1,0]
	v_pk_add_f32 v[58:59], v[58:59], 1.0 op_sel_hi:[1,0]
	v_rcp_f32_e32 v60, v60
	v_rcp_f32_e32 v61, v61
	v_rcp_f32_e32 v62, v62
	v_rcp_f32_e32 v63, v63
	v_rcp_f32_e32 v56, v56
	v_rcp_f32_e32 v57, v57
	v_rcp_f32_e32 v58, v58
	v_rcp_f32_e32 v59, v59
	v_pk_fma_f32 v[60:61], v[60:61], s[20:21], 0.5 op_sel_hi:[1,0,0]
	v_pk_fma_f32 v[62:63], v[62:63], s[20:21], 0.5 op_sel_hi:[1,0,0]
	v_pk_fma_f32 v[56:57], v[56:57], s[20:21], 0.5 op_sel_hi:[1,0,0]
	v_pk_fma_f32 v[58:59], v[58:59], s[20:21], 0.5 op_sel_hi:[1,0,0]
	v_cvt_u32_f32_e32 v128, v60
	v_cvt_u32_f32_e32 v129, v56
	v_cvt_u32_f32_sdwa v128, v61 dst_sel:BYTE_1 dst_unused:UNUSED_PRESERVE src0_sel:DWORD
	v_cvt_u32_f32_sdwa v129, v57 dst_sel:BYTE_1 dst_unused:UNUSED_PRESERVE src0_sel:DWORD
	v_cvt_u32_f32_sdwa v128, v62 dst_sel:BYTE_2 dst_unused:UNUSED_PRESERVE src0_sel:DWORD
	v_cvt_u32_f32_sdwa v129, v58 dst_sel:BYTE_2 dst_unused:UNUSED_PRESERVE src0_sel:DWORD
	v_cvt_u32_f32_sdwa v128, v63 dst_sel:BYTE_3 dst_unused:UNUSED_PRESERVE src0_sel:DWORD
	v_cvt_u32_f32_sdwa v129, v59 dst_sel:BYTE_3 dst_unused:UNUSED_PRESERVE src0_sel:DWORD
	s_nop 0
	ds_bpermute_b32 v128, v199, v128
	ds_bpermute_b32 v129, v199, v129
	s_waitcnt lgkmcnt(4)
	global_store_dwordx2 v155, v[134:135], s[4:5]
	v_pk_fma_f32 v[52:53], v[52:53], vcc, v[144:145] op_sel_hi:[1,0,1]
	v_pk_fma_f32 v[54:55], v[54:55], vcc, v[146:147] op_sel_hi:[1,0,1]
	v_pk_fma_f32 v[48:49], v[48:49], vcc, v[148:149] op_sel_hi:[1,0,1]
	v_pk_fma_f32 v[50:51], v[50:51], vcc, v[150:151] op_sel_hi:[1,0,1]
	v_exp_f32_e32 v52, v52
	v_exp_f32_e32 v53, v53
	v_exp_f32_e32 v54, v54
	v_exp_f32_e32 v55, v55
	v_exp_f32_e32 v48, v48
	v_exp_f32_e32 v49, v49
	v_exp_f32_e32 v50, v50
	v_exp_f32_e32 v51, v51
	v_pk_add_f32 v[52:53], v[52:53], 1.0 op_sel_hi:[1,0]
	v_pk_add_f32 v[54:55], v[54:55], 1.0 op_sel_hi:[1,0]
	v_pk_add_f32 v[48:49], v[48:49], 1.0 op_sel_hi:[1,0]
	v_pk_add_f32 v[50:51], v[50:51], 1.0 op_sel_hi:[1,0]
	v_rcp_f32_e32 v52, v52
	v_rcp_f32_e32 v53, v53
	v_rcp_f32_e32 v54, v54
	v_rcp_f32_e32 v55, v55
	v_rcp_f32_e32 v48, v48
	v_rcp_f32_e32 v49, v49
	v_rcp_f32_e32 v50, v50
	v_rcp_f32_e32 v51, v51
	v_pk_fma_f32 v[52:53], v[52:53], s[20:21], 0.5 op_sel_hi:[1,0,0]
	v_pk_fma_f32 v[54:55], v[54:55], s[20:21], 0.5 op_sel_hi:[1,0,0]
	v_pk_fma_f32 v[48:49], v[48:49], s[20:21], 0.5 op_sel_hi:[1,0,0]
	v_pk_fma_f32 v[50:51], v[50:51], s[20:21], 0.5 op_sel_hi:[1,0,0]
	v_cvt_u32_f32_e32 v130, v52
	v_cvt_u32_f32_e32 v131, v48
	v_cvt_u32_f32_sdwa v130, v53 dst_sel:BYTE_1 dst_unused:UNUSED_PRESERVE src0_sel:DWORD
	v_cvt_u32_f32_sdwa v131, v49 dst_sel:BYTE_1 dst_unused:UNUSED_PRESERVE src0_sel:DWORD
	v_cvt_u32_f32_sdwa v130, v54 dst_sel:BYTE_2 dst_unused:UNUSED_PRESERVE src0_sel:DWORD
	v_cvt_u32_f32_sdwa v131, v50 dst_sel:BYTE_2 dst_unused:UNUSED_PRESERVE src0_sel:DWORD
	v_cvt_u32_f32_sdwa v130, v55 dst_sel:BYTE_3 dst_unused:UNUSED_PRESERVE src0_sel:DWORD
	v_cvt_u32_f32_sdwa v131, v51 dst_sel:BYTE_3 dst_unused:UNUSED_PRESERVE src0_sel:DWORD
	s_nop 0
	ds_bpermute_b32 v130, v199, v130
	ds_bpermute_b32 v131, v199, v131
	s_waitcnt lgkmcnt(4)
	global_store_dwordx2 v155, v[160:161], s[4:5] offset:128
	v_pk_fma_f32 v[44:45], v[44:45], vcc, v[136:137] op_sel_hi:[1,0,1]
	v_pk_fma_f32 v[46:47], v[46:47], vcc, v[138:139] op_sel_hi:[1,0,1]
	v_pk_fma_f32 v[40:41], v[40:41], vcc, v[140:141] op_sel_hi:[1,0,1]
	v_pk_fma_f32 v[42:43], v[42:43], vcc, v[142:143] op_sel_hi:[1,0,1]
	v_exp_f32_e32 v44, v44
	v_exp_f32_e32 v45, v45
	v_exp_f32_e32 v46, v46
	v_exp_f32_e32 v47, v47
	v_exp_f32_e32 v40, v40
	v_exp_f32_e32 v41, v41
	v_exp_f32_e32 v42, v42
	v_exp_f32_e32 v43, v43
	v_pk_add_f32 v[44:45], v[44:45], 1.0 op_sel_hi:[1,0]
	v_pk_add_f32 v[46:47], v[46:47], 1.0 op_sel_hi:[1,0]
	v_pk_add_f32 v[40:41], v[40:41], 1.0 op_sel_hi:[1,0]
	v_pk_add_f32 v[42:43], v[42:43], 1.0 op_sel_hi:[1,0]
	v_rcp_f32_e32 v44, v44
	v_rcp_f32_e32 v45, v45
	v_rcp_f32_e32 v46, v46
	v_rcp_f32_e32 v47, v47
	v_rcp_f32_e32 v40, v40
	v_rcp_f32_e32 v41, v41
	v_rcp_f32_e32 v42, v42
	v_rcp_f32_e32 v43, v43
	v_pk_fma_f32 v[44:45], v[44:45], s[20:21], 0.5 op_sel_hi:[1,0,0]
	v_pk_fma_f32 v[46:47], v[46:47], s[20:21], 0.5 op_sel_hi:[1,0,0]
	v_pk_fma_f32 v[40:41], v[40:41], s[20:21], 0.5 op_sel_hi:[1,0,0]
	v_pk_fma_f32 v[42:43], v[42:43], s[20:21], 0.5 op_sel_hi:[1,0,0]
	v_cvt_u32_f32_e32 v134, v44
	v_cvt_u32_f32_e32 v135, v40
	v_cvt_u32_f32_sdwa v134, v45 dst_sel:BYTE_1 dst_unused:UNUSED_PRESERVE src0_sel:DWORD
	v_cvt_u32_f32_sdwa v135, v41 dst_sel:BYTE_1 dst_unused:UNUSED_PRESERVE src0_sel:DWORD
	v_cvt_u32_f32_sdwa v134, v46 dst_sel:BYTE_2 dst_unused:UNUSED_PRESERVE src0_sel:DWORD
	v_cvt_u32_f32_sdwa v135, v42 dst_sel:BYTE_2 dst_unused:UNUSED_PRESERVE src0_sel:DWORD
	v_cvt_u32_f32_sdwa v134, v47 dst_sel:BYTE_3 dst_unused:UNUSED_PRESERVE src0_sel:DWORD
	v_cvt_u32_f32_sdwa v135, v43 dst_sel:BYTE_3 dst_unused:UNUSED_PRESERVE src0_sel:DWORD
	s_nop 0
	ds_bpermute_b32 v134, v199, v134
	ds_bpermute_b32 v135, v199, v135
	s_waitcnt lgkmcnt(4)
	global_store_dwordx2 v156, v[128:129], s[4:5]
	v_pk_fma_f32 v[36:37], v[36:37], vcc, v[144:145] op_sel_hi:[1,0,1]
	v_pk_fma_f32 v[38:39], v[38:39], vcc, v[146:147] op_sel_hi:[1,0,1]
	v_pk_fma_f32 v[32:33], v[32:33], vcc, v[148:149] op_sel_hi:[1,0,1]
	v_pk_fma_f32 v[34:35], v[34:35], vcc, v[150:151] op_sel_hi:[1,0,1]
	v_exp_f32_e32 v36, v36
	v_exp_f32_e32 v37, v37
	v_exp_f32_e32 v38, v38
	v_exp_f32_e32 v39, v39
	v_exp_f32_e32 v32, v32
	v_exp_f32_e32 v33, v33
	v_exp_f32_e32 v34, v34
	v_exp_f32_e32 v35, v35
	v_pk_add_f32 v[36:37], v[36:37], 1.0 op_sel_hi:[1,0]
	v_pk_add_f32 v[38:39], v[38:39], 1.0 op_sel_hi:[1,0]
	v_pk_add_f32 v[32:33], v[32:33], 1.0 op_sel_hi:[1,0]
	v_pk_add_f32 v[34:35], v[34:35], 1.0 op_sel_hi:[1,0]
	v_rcp_f32_e32 v36, v36
	v_rcp_f32_e32 v37, v37
	v_rcp_f32_e32 v38, v38
	v_rcp_f32_e32 v39, v39
	v_rcp_f32_e32 v32, v32
	v_rcp_f32_e32 v33, v33
	v_rcp_f32_e32 v34, v34
	v_rcp_f32_e32 v35, v35
	v_pk_fma_f32 v[36:37], v[36:37], s[20:21], 0.5 op_sel_hi:[1,0,0]
	v_pk_fma_f32 v[38:39], v[38:39], s[20:21], 0.5 op_sel_hi:[1,0,0]
	v_pk_fma_f32 v[32:33], v[32:33], s[20:21], 0.5 op_sel_hi:[1,0,0]
	v_pk_fma_f32 v[34:35], v[34:35], s[20:21], 0.5 op_sel_hi:[1,0,0]
	v_cvt_u32_f32_e32 v160, v36
	v_cvt_u32_f32_e32 v161, v32
	v_cvt_u32_f32_sdwa v160, v37 dst_sel:BYTE_1 dst_unused:UNUSED_PRESERVE src0_sel:DWORD
	v_cvt_u32_f32_sdwa v161, v33 dst_sel:BYTE_1 dst_unused:UNUSED_PRESERVE src0_sel:DWORD
	v_cvt_u32_f32_sdwa v160, v38 dst_sel:BYTE_2 dst_unused:UNUSED_PRESERVE src0_sel:DWORD
	v_cvt_u32_f32_sdwa v161, v34 dst_sel:BYTE_2 dst_unused:UNUSED_PRESERVE src0_sel:DWORD
	v_cvt_u32_f32_sdwa v160, v39 dst_sel:BYTE_3 dst_unused:UNUSED_PRESERVE src0_sel:DWORD
	v_cvt_u32_f32_sdwa v161, v35 dst_sel:BYTE_3 dst_unused:UNUSED_PRESERVE src0_sel:DWORD
	s_nop 0
	ds_bpermute_b32 v160, v199, v160
	ds_bpermute_b32 v161, v199, v161
	s_waitcnt lgkmcnt(4)
	global_store_dwordx2 v156, v[130:131], s[4:5] offset:128
	v_pk_fma_f32 v[28:29], v[28:29], vcc, v[136:137] op_sel_hi:[1,0,1]
	v_pk_fma_f32 v[30:31], v[30:31], vcc, v[138:139] op_sel_hi:[1,0,1]
	v_pk_fma_f32 v[24:25], v[24:25], vcc, v[140:141] op_sel_hi:[1,0,1]
	v_pk_fma_f32 v[26:27], v[26:27], vcc, v[142:143] op_sel_hi:[1,0,1]
	v_exp_f32_e32 v28, v28
	v_exp_f32_e32 v29, v29
	v_exp_f32_e32 v30, v30
	v_exp_f32_e32 v31, v31
	v_exp_f32_e32 v24, v24
	v_exp_f32_e32 v25, v25
	v_exp_f32_e32 v26, v26
	v_exp_f32_e32 v27, v27
	v_pk_add_f32 v[28:29], v[28:29], 1.0 op_sel_hi:[1,0]
	v_pk_add_f32 v[30:31], v[30:31], 1.0 op_sel_hi:[1,0]
	v_pk_add_f32 v[24:25], v[24:25], 1.0 op_sel_hi:[1,0]
	v_pk_add_f32 v[26:27], v[26:27], 1.0 op_sel_hi:[1,0]
	v_rcp_f32_e32 v28, v28
	v_rcp_f32_e32 v29, v29
	v_rcp_f32_e32 v30, v30
	v_rcp_f32_e32 v31, v31
	v_rcp_f32_e32 v24, v24
	v_rcp_f32_e32 v25, v25
	v_rcp_f32_e32 v26, v26
	v_rcp_f32_e32 v27, v27
	v_pk_fma_f32 v[28:29], v[28:29], s[20:21], 0.5 op_sel_hi:[1,0,0]
	v_pk_fma_f32 v[30:31], v[30:31], s[20:21], 0.5 op_sel_hi:[1,0,0]
	v_pk_fma_f32 v[24:25], v[24:25], s[20:21], 0.5 op_sel_hi:[1,0,0]
	v_pk_fma_f32 v[26:27], v[26:27], s[20:21], 0.5 op_sel_hi:[1,0,0]
	v_cvt_u32_f32_e32 v128, v28
	v_cvt_u32_f32_e32 v129, v24
	v_cvt_u32_f32_sdwa v128, v29 dst_sel:BYTE_1 dst_unused:UNUSED_PRESERVE src0_sel:DWORD
	v_cvt_u32_f32_sdwa v129, v25 dst_sel:BYTE_1 dst_unused:UNUSED_PRESERVE src0_sel:DWORD
	v_cvt_u32_f32_sdwa v128, v30 dst_sel:BYTE_2 dst_unused:UNUSED_PRESERVE src0_sel:DWORD
	v_cvt_u32_f32_sdwa v129, v26 dst_sel:BYTE_2 dst_unused:UNUSED_PRESERVE src0_sel:DWORD
	v_cvt_u32_f32_sdwa v128, v31 dst_sel:BYTE_3 dst_unused:UNUSED_PRESERVE src0_sel:DWORD
	v_cvt_u32_f32_sdwa v129, v27 dst_sel:BYTE_3 dst_unused:UNUSED_PRESERVE src0_sel:DWORD
	s_nop 0
	ds_bpermute_b32 v128, v199, v128
	ds_bpermute_b32 v129, v199, v129
	s_waitcnt lgkmcnt(4)
	global_store_dwordx2 v157, v[134:135], s[4:5]
	v_pk_fma_f32 v[20:21], v[20:21], vcc, v[144:145] op_sel_hi:[1,0,1]
	v_pk_fma_f32 v[22:23], v[22:23], vcc, v[146:147] op_sel_hi:[1,0,1]
	v_pk_fma_f32 v[16:17], v[16:17], vcc, v[148:149] op_sel_hi:[1,0,1]
	v_pk_fma_f32 v[18:19], v[18:19], vcc, v[150:151] op_sel_hi:[1,0,1]
	v_exp_f32_e32 v20, v20
	v_exp_f32_e32 v21, v21
	v_exp_f32_e32 v22, v22
	v_exp_f32_e32 v23, v23
	v_exp_f32_e32 v16, v16
	v_exp_f32_e32 v17, v17
	v_exp_f32_e32 v18, v18
	v_exp_f32_e32 v19, v19
	v_pk_add_f32 v[20:21], v[20:21], 1.0 op_sel_hi:[1,0]
	v_pk_add_f32 v[22:23], v[22:23], 1.0 op_sel_hi:[1,0]
	v_pk_add_f32 v[16:17], v[16:17], 1.0 op_sel_hi:[1,0]
	v_pk_add_f32 v[18:19], v[18:19], 1.0 op_sel_hi:[1,0]
	v_rcp_f32_e32 v20, v20
	v_rcp_f32_e32 v21, v21
	v_rcp_f32_e32 v22, v22
	v_rcp_f32_e32 v23, v23
	v_rcp_f32_e32 v16, v16
	v_rcp_f32_e32 v17, v17
	v_rcp_f32_e32 v18, v18
	v_rcp_f32_e32 v19, v19
	v_pk_fma_f32 v[20:21], v[20:21], s[20:21], 0.5 op_sel_hi:[1,0,0]
	v_pk_fma_f32 v[22:23], v[22:23], s[20:21], 0.5 op_sel_hi:[1,0,0]
	v_pk_fma_f32 v[16:17], v[16:17], s[20:21], 0.5 op_sel_hi:[1,0,0]
	v_pk_fma_f32 v[18:19], v[18:19], s[20:21], 0.5 op_sel_hi:[1,0,0]
	v_cvt_u32_f32_e32 v130, v20
	v_cvt_u32_f32_e32 v131, v16
	v_cvt_u32_f32_sdwa v130, v21 dst_sel:BYTE_1 dst_unused:UNUSED_PRESERVE src0_sel:DWORD
	v_cvt_u32_f32_sdwa v131, v17 dst_sel:BYTE_1 dst_unused:UNUSED_PRESERVE src0_sel:DWORD
	v_cvt_u32_f32_sdwa v130, v22 dst_sel:BYTE_2 dst_unused:UNUSED_PRESERVE src0_sel:DWORD
	v_cvt_u32_f32_sdwa v131, v18 dst_sel:BYTE_2 dst_unused:UNUSED_PRESERVE src0_sel:DWORD
	v_cvt_u32_f32_sdwa v130, v23 dst_sel:BYTE_3 dst_unused:UNUSED_PRESERVE src0_sel:DWORD
	v_cvt_u32_f32_sdwa v131, v19 dst_sel:BYTE_3 dst_unused:UNUSED_PRESERVE src0_sel:DWORD
	s_nop 0
	ds_bpermute_b32 v130, v199, v130
	ds_bpermute_b32 v131, v199, v131
	s_waitcnt lgkmcnt(4)
	global_store_dwordx2 v157, v[160:161], s[4:5] offset:128
	v_pk_fma_f32 v[12:13], v[12:13], vcc, v[136:137] op_sel_hi:[1,0,1]
	v_pk_fma_f32 v[14:15], v[14:15], vcc, v[138:139] op_sel_hi:[1,0,1]
	v_pk_fma_f32 v[8:9], v[8:9], vcc, v[140:141] op_sel_hi:[1,0,1]
	v_pk_fma_f32 v[10:11], v[10:11], vcc, v[142:143] op_sel_hi:[1,0,1]
	v_exp_f32_e32 v12, v12
	v_exp_f32_e32 v13, v13
	v_exp_f32_e32 v14, v14
	v_exp_f32_e32 v15, v15
	v_exp_f32_e32 v8, v8
	v_exp_f32_e32 v9, v9
	v_exp_f32_e32 v10, v10
	v_exp_f32_e32 v11, v11
	v_pk_add_f32 v[12:13], v[12:13], 1.0 op_sel_hi:[1,0]
	v_pk_add_f32 v[14:15], v[14:15], 1.0 op_sel_hi:[1,0]
	v_pk_add_f32 v[8:9], v[8:9], 1.0 op_sel_hi:[1,0]
	v_pk_add_f32 v[10:11], v[10:11], 1.0 op_sel_hi:[1,0]
	v_rcp_f32_e32 v12, v12
	v_rcp_f32_e32 v13, v13
	v_rcp_f32_e32 v14, v14
	v_rcp_f32_e32 v15, v15
	v_rcp_f32_e32 v8, v8
	v_rcp_f32_e32 v9, v9
	v_rcp_f32_e32 v10, v10
	v_rcp_f32_e32 v11, v11
	v_pk_fma_f32 v[12:13], v[12:13], s[20:21], 0.5 op_sel_hi:[1,0,0]
	v_pk_fma_f32 v[14:15], v[14:15], s[20:21], 0.5 op_sel_hi:[1,0,0]
	v_pk_fma_f32 v[8:9], v[8:9], s[20:21], 0.5 op_sel_hi:[1,0,0]
	v_pk_fma_f32 v[10:11], v[10:11], s[20:21], 0.5 op_sel_hi:[1,0,0]
	v_cvt_u32_f32_e32 v134, v12
	v_cvt_u32_f32_e32 v135, v8
	v_cvt_u32_f32_sdwa v134, v13 dst_sel:BYTE_1 dst_unused:UNUSED_PRESERVE src0_sel:DWORD
	v_cvt_u32_f32_sdwa v135, v9 dst_sel:BYTE_1 dst_unused:UNUSED_PRESERVE src0_sel:DWORD
	v_cvt_u32_f32_sdwa v134, v14 dst_sel:BYTE_2 dst_unused:UNUSED_PRESERVE src0_sel:DWORD
	v_cvt_u32_f32_sdwa v135, v10 dst_sel:BYTE_2 dst_unused:UNUSED_PRESERVE src0_sel:DWORD
	v_cvt_u32_f32_sdwa v134, v15 dst_sel:BYTE_3 dst_unused:UNUSED_PRESERVE src0_sel:DWORD
	v_cvt_u32_f32_sdwa v135, v11 dst_sel:BYTE_3 dst_unused:UNUSED_PRESERVE src0_sel:DWORD
	s_nop 0
	ds_bpermute_b32 v134, v199, v134
	ds_bpermute_b32 v135, v199, v135
	s_waitcnt lgkmcnt(4)
	global_store_dwordx2 v158, v[128:129], s[4:5]
	v_pk_fma_f32 v[4:5], v[4:5], vcc, v[144:145] op_sel_hi:[1,0,1]
	v_pk_fma_f32 v[6:7], v[6:7], vcc, v[146:147] op_sel_hi:[1,0,1]
	v_pk_fma_f32 v[0:1], v[0:1], vcc, v[148:149] op_sel_hi:[1,0,1]
	v_pk_fma_f32 v[2:3], v[2:3], vcc, v[150:151] op_sel_hi:[1,0,1]
	v_exp_f32_e32 v4, v4
	v_exp_f32_e32 v5, v5
	v_exp_f32_e32 v6, v6
	v_exp_f32_e32 v7, v7
	v_exp_f32_e32 v0, v0
	v_exp_f32_e32 v1, v1
	v_exp_f32_e32 v2, v2
	v_exp_f32_e32 v3, v3
	v_pk_add_f32 v[4:5], v[4:5], 1.0 op_sel_hi:[1,0]
	v_pk_add_f32 v[6:7], v[6:7], 1.0 op_sel_hi:[1,0]
	v_pk_add_f32 v[0:1], v[0:1], 1.0 op_sel_hi:[1,0]
	v_pk_add_f32 v[2:3], v[2:3], 1.0 op_sel_hi:[1,0]
	v_rcp_f32_e32 v4, v4
	v_rcp_f32_e32 v5, v5
	v_rcp_f32_e32 v6, v6
	v_rcp_f32_e32 v7, v7
	v_rcp_f32_e32 v0, v0
	v_rcp_f32_e32 v1, v1
	v_rcp_f32_e32 v2, v2
	v_rcp_f32_e32 v3, v3
	v_pk_fma_f32 v[4:5], v[4:5], s[20:21], 0.5 op_sel_hi:[1,0,0]
	v_pk_fma_f32 v[6:7], v[6:7], s[20:21], 0.5 op_sel_hi:[1,0,0]
	v_pk_fma_f32 v[0:1], v[0:1], s[20:21], 0.5 op_sel_hi:[1,0,0]
	v_pk_fma_f32 v[2:3], v[2:3], s[20:21], 0.5 op_sel_hi:[1,0,0]
	v_cvt_u32_f32_e32 v160, v4
	v_cvt_u32_f32_e32 v161, v0
	v_cvt_u32_f32_sdwa v160, v5 dst_sel:BYTE_1 dst_unused:UNUSED_PRESERVE src0_sel:DWORD
	v_cvt_u32_f32_sdwa v161, v1 dst_sel:BYTE_1 dst_unused:UNUSED_PRESERVE src0_sel:DWORD
	v_cvt_u32_f32_sdwa v160, v6 dst_sel:BYTE_2 dst_unused:UNUSED_PRESERVE src0_sel:DWORD
	v_cvt_u32_f32_sdwa v161, v2 dst_sel:BYTE_2 dst_unused:UNUSED_PRESERVE src0_sel:DWORD
	v_cvt_u32_f32_sdwa v160, v7 dst_sel:BYTE_3 dst_unused:UNUSED_PRESERVE src0_sel:DWORD
	v_cvt_u32_f32_sdwa v161, v3 dst_sel:BYTE_3 dst_unused:UNUSED_PRESERVE src0_sel:DWORD
	s_nop 0
	ds_bpermute_b32 v160, v199, v160
	ds_bpermute_b32 v161, v199, v161
	s_waitcnt lgkmcnt(4)
	global_store_dwordx2 v158, v[130:131], s[4:5] offset:128
	s_waitcnt lgkmcnt(2)
	global_store_dwordx2 v159, v[134:135], s[4:5]
	s_waitcnt lgkmcnt(0)
	global_store_dwordx2 v159, v[160:161], s[4:5] offset:128
	s_mov_b64 s[4:5], 0
